# HGRN2 core chunk prefetch: 80 64-bit VALU address ops per chunk replaced by per-unit 32-bit lane offsets + scalar chunk bases (saddr-form loads)
# speedup vs baseline: 1.0127x; 1.0127x over previous
; template <int DK, int DVS, bool RET> ...
;     ...
;     GLA_LOAD(0);
; __global__ void __launch_bounds__(512) mk_fwd(Params P) {
;     ...
;             for (int L = bid; L < 256; L += G) {
;                 const int slice = L & 3, dir = (L >> 2) & 1, hh = (L >> 3) & 7, bq = L >> 6;
;                 gla_unit<128, 32, false>(lds, bq, hh, dir, slice, Qb, nullptr, Vb, LF, dir ? OB : OF, 0.f, 1024, hh * 128 + slice * 32, tid);
.LBB0_52:
	s_bfe_i32 s36, s49, 0x10002
	s_bfe_u32 s63, s49, 0x10002
	s_ashr_i32 s40, s49, 6
	s_cmp_eq_u32 s63, 0
	s_cselect_b64 s[30:31], -1, 0
	s_and_b64 s[42:43], s[30:31], exec
	s_mov_b32 s42, 0x18b69000
	s_cselect_b32 s42, s42, 0x1ad69000
	s_add_u32 s56, s0, s42
	s_addc_u32 s57, s1, 0
	s_lshl_b32 s42, s49, 4
	s_and_b32 s66, s42, 0x380
	s_lshl_b32 s42, s49, 5
	s_and_b32 s42, s42, 0x60
	s_mov_b32 s41, 0
	s_or_b32 s62, s66, s42
	s_mul_hi_i32 s43, s40, 0x1100
	s_mul_i32 s42, s40, 0x1100
	s_and_b32 s40, s36, 0xc0
	s_or_b64 s[44:45], s[40:41], s[42:43]
	s_lshl_b32 s36, s63, 12
	s_add_u32 s36, s3, s36
	v_sub_u32_e32 v28, 63, v79
	s_addc_u32 s40, s48, 0
	s_lshl_b32 s63, s66, 2
	v_cndmask_b32_e64 v28, v28, v79, s[30:31]
	s_add_u32 s64, s36, s63
	v_ashrrev_i32_e32 v29, 31, v28
	s_addc_u32 s65, s40, 0
	s_lshl_b32 s36, s66, 1
	v_lshl_add_u64 v[30:31], s[44:45], 0, v[28:29]
	v_lshl_add_u64 v[24:25], v[12:13], 0, s[36:37]
	v_lshlrev_b64 v[32:33], 13, v[30:31]
	v_lshlrev_b64 v[30:31], 11, v[30:31]
	v_sub_u32_e32 v0, 63, v77
	v_lshl_add_u64 v[34:35], v[24:25], 0, v[30:31]
	v_sub_u32_e32 v30, 63, v80
	v_cndmask_b32_e64 v20, v0, v77, s[30:31]
	v_sub_u32_e32 v4, 63, v78
	v_cndmask_b32_e64 v30, v30, v80, s[30:31]
	v_ashrrev_i32_e32 v21, 31, v20
	v_cndmask_b32_e64 v26, v4, v78, s[30:31]
	v_ashrrev_i32_e32 v31, 31, v30
	v_lshl_add_u64 v[0:1], s[44:45], 0, v[20:21]
	v_ashrrev_i32_e32 v27, 31, v26
	v_lshl_add_u64 v[36:37], s[44:45], 0, v[30:31]
	v_lshl_add_u64 v[22:23], v[10:11], 2, s[64:65]
	v_lshlrev_b64 v[2:3], 13, v[0:1]
	v_lshl_add_u64 v[4:5], s[44:45], 0, v[26:27]
	v_lshlrev_b64 v[38:39], 13, v[36:37]
	v_lshlrev_b64 v[36:37], 11, v[36:37]
	v_readlane_b32 s59, v253, 62
	v_readlane_b32 s51, v254, 0
	v_readlane_b32 s47, v254, 2
	s_mov_b32 s50, s37
	v_readlane_b32 s46, v253, 63
	v_readlane_b32 s61, v254, 1
	v_readlane_b32 s60, v254, 3
	v_lshl_add_u64 v[2:3], v[22:23], 0, v[2:3]
	v_lshlrev_b64 v[0:1], 11, v[0:1]
	v_lshlrev_b64 v[6:7], 13, v[4:5]
	v_lshlrev_b64 v[4:5], 11, v[4:5]
	v_lshl_add_u64 v[36:37], v[24:25], 0, v[36:37]
	v_lshl_add_u64 v[0:1], v[24:25], 0, v[0:1]
	v_lshl_add_u64 v[6:7], v[22:23], 0, v[6:7]
	v_lshl_add_u64 v[4:5], v[24:25], 0, v[4:5]
	v_lshl_add_u64 v[32:33], v[22:23], 0, v[32:33]
	v_lshl_add_u64 v[38:39], v[22:23], 0, v[38:39]
	global_load_dword v132, v[2:3], off
	global_load_ushort v133, v[0:1], off
	global_load_dword v134, v[6:7], off
	global_load_ushort v135, v[4:5], off
	global_load_dword v136, v[32:33], off
	global_load_ushort v137, v[34:35], off
	global_load_dword v138, v[38:39], off
	global_load_ushort v139, v[36:37], off
	v_sub_u32_e32 v36, 63, v83
	v_cndmask_b32_e64 v36, v36, v83, s[30:31]
	v_ashrrev_i32_e32 v37, 31, v36
	v_lshl_add_u64 v[38:39], s[44:45], 0, v[36:37]
	v_lshlrev_b64 v[40:41], 13, v[38:39]
	v_lshlrev_b64 v[38:39], 11, v[38:39]
	v_sub_u32_e32 v0, 63, v81
	v_lshl_add_u64 v[42:43], v[24:25], 0, v[38:39]
	v_sub_u32_e32 v38, 63, v84
	v_cndmask_b32_e64 v32, v0, v81, s[30:31]
	v_sub_u32_e32 v4, 63, v82
	v_cndmask_b32_e64 v38, v38, v84, s[30:31]
	v_ashrrev_i32_e32 v33, 31, v32
	v_cndmask_b32_e64 v34, v4, v82, s[30:31]
	v_ashrrev_i32_e32 v39, 31, v38
	v_lshl_add_u64 v[0:1], s[44:45], 0, v[32:33]
	v_ashrrev_i32_e32 v35, 31, v34
	v_lshl_add_u64 v[44:45], s[44:45], 0, v[38:39]
	v_lshlrev_b64 v[2:3], 13, v[0:1]
	v_lshl_add_u64 v[4:5], s[44:45], 0, v[34:35]
	v_lshlrev_b64 v[46:47], 13, v[44:45]
	v_lshlrev_b64 v[44:45], 11, v[44:45]
	v_lshl_add_u64 v[2:3], v[22:23], 0, v[2:3]
	v_lshlrev_b64 v[0:1], 11, v[0:1]
	v_lshlrev_b64 v[6:7], 13, v[4:5]
	v_lshlrev_b64 v[4:5], 11, v[4:5]
	v_lshl_add_u64 v[44:45], v[24:25], 0, v[44:45]
	v_lshl_add_u64 v[0:1], v[24:25], 0, v[0:1]
	v_lshl_add_u64 v[6:7], v[22:23], 0, v[6:7]
	v_lshl_add_u64 v[4:5], v[24:25], 0, v[4:5]
	v_lshl_add_u64 v[40:41], v[22:23], 0, v[40:41]
	v_lshl_add_u64 v[46:47], v[22:23], 0, v[46:47]
	global_load_dword v140, v[2:3], off
	global_load_ushort v141, v[0:1], off
	global_load_dword v142, v[6:7], off
	global_load_ushort v143, v[4:5], off
	global_load_dword v147, v[40:41], off
	global_load_ushort v150, v[42:43], off
	global_load_dword v151, v[46:47], off
	global_load_ushort v162, v[44:45], off
	v_sub_u32_e32 v44, 63, v87
	v_cndmask_b32_e64 v44, v44, v87, s[30:31]
	v_ashrrev_i32_e32 v45, 31, v44
	v_lshl_add_u64 v[46:47], s[44:45], 0, v[44:45]
	v_lshlrev_b64 v[48:49], 13, v[46:47]
	v_lshlrev_b64 v[46:47], 11, v[46:47]
	v_sub_u32_e32 v0, 63, v85
	v_lshl_add_u64 v[50:51], v[24:25], 0, v[46:47]
	v_sub_u32_e32 v46, 63, v88
	v_cndmask_b32_e64 v40, v0, v85, s[30:31]
	v_sub_u32_e32 v4, 63, v86
	v_cndmask_b32_e64 v46, v46, v88, s[30:31]
	v_ashrrev_i32_e32 v41, 31, v40
	v_cndmask_b32_e64 v42, v4, v86, s[30:31]
	v_ashrrev_i32_e32 v47, 31, v46
	v_lshl_add_u64 v[0:1], s[44:45], 0, v[40:41]
	v_ashrrev_i32_e32 v43, 31, v42
	v_lshl_add_u64 v[52:53], s[44:45], 0, v[46:47]
	v_lshlrev_b64 v[2:3], 13, v[0:1]
	v_lshl_add_u64 v[4:5], s[44:45], 0, v[42:43]
	v_lshlrev_b64 v[54:55], 13, v[52:53]
	v_lshlrev_b64 v[52:53], 11, v[52:53]
	v_lshl_add_u64 v[2:3], v[22:23], 0, v[2:3]
	v_lshlrev_b64 v[0:1], 11, v[0:1]
	v_lshlrev_b64 v[6:7], 13, v[4:5]
	v_lshlrev_b64 v[4:5], 11, v[4:5]
	v_lshl_add_u64 v[52:53], v[24:25], 0, v[52:53]
	v_lshl_add_u64 v[0:1], v[24:25], 0, v[0:1]
	v_lshl_add_u64 v[6:7], v[22:23], 0, v[6:7]
	v_lshl_add_u64 v[4:5], v[24:25], 0, v[4:5]
	v_lshl_add_u64 v[48:49], v[22:23], 0, v[48:49]
	v_lshl_add_u64 v[54:55], v[22:23], 0, v[54:55]
	global_load_dword v210, v[2:3], off
	global_load_ushort v217, v[0:1], off
	global_load_dword v220, v[6:7], off
	global_load_ushort v221, v[4:5], off
	global_load_dword v222, v[48:49], off
	global_load_ushort v223, v[50:51], off
	global_load_dword v224, v[54:55], off
; #define GAS __attribute__((address_space(1)))
; template <int DK, int DVS, bool RET> ...
;     ...
;     const int wid = tid >> 6, lane = tid & 63, l16 = lane & 15, quad = lane >> 4;
;     const int tr = wid >> 1, tv = wid / WPV, kt0 = (wid % WPV) * TPW;
;     const int vtr = (int)aVI + (8 * quad + (l16 >> 2)) * (LV * 2) + 8 * (lane & 3);
;     const int ktr = (int)aKD + (8 * quad + (l16 >> 2)) * (LK * 2) + 8 * (lane & 3);
;     ...
;     f32x4 st[TPW];
; #pragma unroll
;     for (int t = 0; t < TPW; ++t) st[t] = (f32x4){0.f, 0.f, 0.f, 0.f};
;     ...
;     typedef short vvec_t __attribute__((ext_vector_type(VPT)));
;     constexpr int NQV = RET ? 4 : 1, NLC = RET ? 1 : PPT;
;     bf16x8 qv[NQV], kv[NQV]; float lc[NLC]; bf16_t qr[NLC]; vvec_t vraw;
;     const int kx = tid % DK, pg = tid / DK;
;     const GAS bf16_t* Qg = (const GAS bf16_t*)Q; const GAS bf16_t* Kg = (const GAS bf16_t*)Kp; const GAS float* LFg = (const GAS float*)LF; const GAS bf16_t* Vg = (const GAS bf16_t*)V;
	global_load_ushort v225, v[52:53], off
	v_sub_u32_e32 v52, 63, v91
	v_cndmask_b32_e64 v52, v52, v91, s[30:31]
	v_ashrrev_i32_e32 v53, 31, v52
	v_lshl_add_u64 v[54:55], s[44:45], 0, v[52:53]
	v_sub_u32_e32 v0, 63, v89
	v_lshlrev_b64 v[56:57], 13, v[54:55]
	v_lshlrev_b64 v[54:55], 11, v[54:55]
	v_cndmask_b32_e64 v48, v0, v89, s[30:31]
	v_sub_u32_e32 v4, 63, v90
	v_lshl_add_u64 v[58:59], v[24:25], 0, v[54:55]
	v_sub_u32_e32 v54, 63, v92
	v_ashrrev_i32_e32 v49, 31, v48
	v_cndmask_b32_e64 v50, v4, v90, s[30:31]
	v_cndmask_b32_e64 v54, v54, v92, s[30:31]
	v_lshl_add_u64 v[0:1], s[44:45], 0, v[48:49]
	v_ashrrev_i32_e32 v51, 31, v50
	v_ashrrev_i32_e32 v55, 31, v54
	v_lshlrev_b64 v[2:3], 13, v[0:1]
	v_lshl_add_u64 v[4:5], s[44:45], 0, v[50:51]
	v_lshl_add_u64 v[60:61], s[44:45], 0, v[54:55]
	v_lshl_add_u64 v[2:3], v[22:23], 0, v[2:3]
	v_lshlrev_b64 v[0:1], 11, v[0:1]
	v_lshlrev_b64 v[6:7], 13, v[4:5]
	v_lshlrev_b64 v[4:5], 11, v[4:5]
	v_lshlrev_b64 v[62:63], 13, v[60:61]
	v_lshlrev_b64 v[60:61], 11, v[60:61]
	v_lshl_add_u64 v[0:1], v[24:25], 0, v[0:1]
	v_lshl_add_u64 v[6:7], v[22:23], 0, v[6:7]
	v_lshl_add_u64 v[4:5], v[24:25], 0, v[4:5]
	v_lshl_add_u64 v[56:57], v[22:23], 0, v[56:57]
	v_lshl_add_u64 v[62:63], v[22:23], 0, v[62:63]
	v_lshl_add_u64 v[60:61], v[24:25], 0, v[60:61]
	global_load_dword v226, v[2:3], off
	global_load_ushort v227, v[0:1], off
	global_load_dword v228, v[6:7], off
	global_load_ushort v229, v[4:5], off
	global_load_dword v230, v[56:57], off
	global_load_ushort v231, v[58:59], off
	global_load_dword v232, v[62:63], off
	global_load_ushort v233, v[60:61], off
	v_sub_u32_e32 v2, 63, v93
	s_lshl_b32 s36, s62, 1
	v_cndmask_b32_e64 v56, v2, v93, s[30:31]
	v_lshlrev_b32_e32 v2, 2, v10
	s_movk_i32 s40, 0x50
	s_add_u32 s44, s56, s36
	v_lshlrev_b32_e32 v1, 1, v9
	v_lshlrev_b32_e32 v0, 1, v8
	v_add_u32_e32 v153, s61, v2
	v_add_u32_e32 v154, s51, v2
	v_mul_lo_u32 v2, v93, s40
	s_addc_u32 s45, s57, 0
	v_add_u32_e32 v4, s50, v1
	v_add_u32_e32 v5, s60, v0
	v_add3_u32 v155, s59, v2, v14
	v_add3_u32 v156, s47, v96, v1
	v_add_u32_e32 v6, s60, v1
	v_add3_u32 v158, s46, v99, v1
	v_lshl_add_u64 v[2:3], s[44:45], 0, v[144:145]
	v_mov_b32_e32 v1, v145
	v_add_u32_e32 v64, s59, v76
	v_lshl_add_u64 v[60:61], v[2:3], 0, v[0:1]
	v_add_u32_e32 v0, s47, v101
	v_add_u32_e32 v2, v5, v102
	v_add_u32_e32 v3, v5, v104
	v_lshlrev_b32_e32 v5, 1, v18
	v_add_u32_e32 v157, v64, v15
	v_add_u32_e32 v159, v64, v100
	v_lshl_add_u32 v1, v8, 2, s51
	v_add_u32_e32 v163, s50, v5
	v_add_u32_e32 v164, s47, v5
	v_lshlrev_b32_e32 v5, 1, v95
	v_cndmask_b32_e64 v62, v251, v97, s[30:31]
	v_cndmask_b32_e64 v64, v252, v105, s[30:31]
	v_cndmask_b32_e64 v66, v198, v107, s[30:31]
	v_cndmask_b32_e64 v68, v114, v109, s[30:31]
	v_add_u32_e32 v211, v0, v102
	v_add_u32_e32 v212, v0, v104
	v_mov_b32_e32 v0, 0
	v_ashrrev_i32_e32 v57, 31, v56
	v_lshl_add_u64 v[58:59], v[16:17], 0, s[36:37]
	v_lshl_add_u32 v152, v146, 2, s61
	v_add_u32_e32 v160, s50, v117
	v_add_u32_e32 v161, s47, v117
	v_add_u32_e32 v165, s50, v118
	v_add_u32_e32 v166, s47, v118
	v_add_u32_e32 v167, s50, v119
	v_add_u32_e32 v168, s47, v119
	v_add_u32_e32 v169, s50, v120
	v_add_u32_e32 v170, s47, v120
	v_add_u32_e32 v171, s50, v121
	v_add_u32_e32 v172, s47, v121
	v_add_u32_e32 v173, s50, v122
	v_add_u32_e32 v174, s47, v122
	v_add_u32_e32 v175, s50, v123
	v_add_u32_e32 v176, s47, v123
	v_add_u32_e32 v177, s50, v124
	v_add_u32_e32 v178, s47, v124
	v_add_u32_e32 v179, s50, v125
	v_add_u32_e32 v180, s47, v125
	v_add_u32_e32 v181, s50, v126
	v_add_u32_e32 v182, s47, v126
	v_add_u32_e32 v183, s50, v127
	v_add_u32_e32 v184, s47, v127
	v_add_u32_e32 v185, s50, v128
	v_add_u32_e32 v199, s47, v128
	v_add_u32_e32 v200, s50, v129
	v_add_u32_e32 v201, s47, v129
	v_add_u32_e32 v202, s50, v130
	v_add_u32_e32 v203, s47, v130
	v_add_u32_e32 v204, s50, v131
	v_add_u32_e32 v205, s47, v131
	v_add3_u32 v206, s46, v19, v5
	v_add3_u32 v207, s46, v106, v5
	v_add3_u32 v208, s46, v108, v5
	v_add3_u32 v209, s46, v250, v5
	v_ashrrev_i32_e32 v63, 31, v62
	v_ashrrev_i32_e32 v65, 31, v64
	v_ashrrev_i32_e32 v67, 31, v66
	v_ashrrev_i32_e32 v69, 31, v68
	v_add_u32_e32 v213, v2, v103
	v_add_u32_e32 v214, v3, v103
	v_add_u32_e32 v215, v4, v94
	v_add_u32_e32 v216, v6, v98
	v_add_u32_e32 v218, v1, v115
	v_add_u32_e32 v219, v1, v116
	s_mov_b32 s36, s41
	v_mov_b32_e32 v1, v0
	v_mov_b32_e32 v2, v0
	v_mov_b32_e32 v3, v0
	v_mov_b32_e32 v4, v0
	v_mov_b32_e32 v5, v0
	v_mov_b32_e32 v6, v0
	v_mov_b32_e32 v7, v0
	v_mov_b32_e32 v71, v0
	v_mov_b32_e32 v72, v0
	v_mov_b32_e32 v73, v0
	v_mov_b32_e32 v74, v0
	v_mov_b32_e32 v75, v0
	v_mov_b32_e32 v234, v0
	v_mov_b32_e32 v70, v0
	v_lshlrev_b32_e32 v22, 2, v10
	v_lshlrev_b32_e32 v23, 1, v10
	v_lshl_add_u32 v21, v20, 11, v23
	v_lshl_add_u32 v20, v20, 13, v22
	v_lshl_add_u32 v27, v26, 11, v23
	v_lshl_add_u32 v26, v26, 13, v22
	v_lshl_add_u32 v29, v28, 11, v23
	v_lshl_add_u32 v28, v28, 13, v22
	v_lshl_add_u32 v31, v30, 11, v23
	v_lshl_add_u32 v30, v30, 13, v22
	v_lshl_add_u32 v33, v32, 11, v23
	v_lshl_add_u32 v32, v32, 13, v22
	v_lshl_add_u32 v35, v34, 11, v23
	v_lshl_add_u32 v34, v34, 13, v22
	v_lshl_add_u32 v37, v36, 11, v23
	v_lshl_add_u32 v36, v36, 13, v22
	v_lshl_add_u32 v39, v38, 11, v23
	v_lshl_add_u32 v38, v38, 13, v22
	v_lshl_add_u32 v41, v40, 11, v23
	v_lshl_add_u32 v40, v40, 13, v22
	v_lshl_add_u32 v43, v42, 11, v23
	v_lshl_add_u32 v42, v42, 13, v22
	v_lshl_add_u32 v45, v44, 11, v23
	v_lshl_add_u32 v44, v44, 13, v22
	v_lshl_add_u32 v47, v46, 11, v23
	v_lshl_add_u32 v46, v46, 13, v22
	v_lshl_add_u32 v49, v48, 11, v23
	v_lshl_add_u32 v48, v48, 13, v22
	v_lshl_add_u32 v51, v50, 11, v23
	v_lshl_add_u32 v50, v50, 13, v22
	v_lshl_add_u32 v53, v52, 11, v23
	v_lshl_add_u32 v52, v52, 13, v22
	v_lshl_add_u32 v55, v54, 11, v23
	v_lshl_add_u32 v54, v54, 13, v22
	s_branch .LBB0_54

; #define LAS __attribute__((address_space(3)))
; template <int DK, int DVS, bool RET> ...
;     ...
;             { const int p = tid >> 3, vg = tid & 7; *(LAS vvec_t*)(VI + p * LV + vg * VPT) = vraw; }
;         }
;         if (step + 1 < 68) GLA_LOAD(step + 1);
.LBB0_56:
	s_or_b64 exec, exec, s[46:47]
	s_add_i32 s40, s36, 1
	s_cmpk_eq_i32 s41, 0xffbd
	s_waitcnt vmcnt(0)
	ds_write_b64 v155, v[70:71]
	s_cbranch_scc1 .LBB0_53
	s_cmp_gt_u32 s36, 2
	s_cselect_b32 s36, 0x46, 2
	s_add_i32 s36, s36, s41
	s_and_b64 s[46:47], s[30:31], exec
	s_cselect_b32 s36, s40, s36
	s_lshl_b32 s36, s36, 6
	s_ashr_i32 s47, s36, 31
	s_add_u32 s46, s42, s36
	s_addc_u32 s47, s43, s47
	s_lshl_b64 s[38:39], s[46:47], 11
	s_add_u32 s38, s38, s90
	s_addc_u32 s39, s39, s91
	s_lshl_b32 s36, s66, 1
	s_add_u32 s38, s38, s36
	s_addc_u32 s39, s39, 0
	s_lshl_b64 s[46:47], s[46:47], 13
	s_add_u32 s46, s46, s64
	s_addc_u32 s47, s47, s65
	global_load_dword v132, v20, s[46:47]
	global_load_ushort v133, v21, s[38:39]
	global_load_dword v134, v26, s[46:47]
	global_load_ushort v135, v27, s[38:39]
	global_load_dword v136, v28, s[46:47]
	global_load_ushort v137, v29, s[38:39]
	global_load_dword v138, v30, s[46:47]
	global_load_ushort v139, v31, s[38:39]
	global_load_dword v140, v32, s[46:47]
	global_load_ushort v141, v33, s[38:39]
	global_load_dword v142, v34, s[46:47]
	global_load_ushort v143, v35, s[38:39]
	global_load_dword v147, v36, s[46:47]
	global_load_ushort v150, v37, s[38:39]
	global_load_dword v151, v38, s[46:47]
	global_load_ushort v162, v39, s[38:39]
	global_load_dword v210, v40, s[46:47]
	global_load_ushort v217, v41, s[38:39]
	global_load_dword v220, v42, s[46:47]
	global_load_ushort v221, v43, s[38:39]
	global_load_dword v222, v44, s[46:47]
	global_load_ushort v223, v45, s[38:39]
	global_load_dword v224, v46, s[46:47]
	global_load_ushort v225, v47, s[38:39]
	global_load_dword v226, v48, s[46:47]
	global_load_ushort v227, v49, s[38:39]
	global_load_dword v228, v50, s[46:47]
	global_load_ushort v229, v51, s[38:39]
	global_load_dword v230, v52, s[46:47]
	global_load_ushort v231, v53, s[38:39]
	global_load_dword v232, v54, s[46:47]
	global_load_ushort v233, v55, s[38:39]
	s_branch .LBB0_53
